# GLA pass A gates: log1p(exp(-|x|)) evaluated as log(u)*e/(u-1) on the f32 log/rcp units instead of the generic double-float expansion
# speedup vs baseline: 1.0145x; 1.0103x over previous
.LBB0_675:
	s_or_b64 exec, exec, s[24:25]
	s_and_b64 s[10:11], vcc, exec
	s_movk_i32 s4, 0x68
	s_cselect_b32 s4, s4, 0x78
	s_add_u32 s10, s8, s4
	s_addc_u32 s11, s9, 0
	s_waitcnt lgkmcnt(0)
	s_barrier
	s_load_dwordx2 s[10:11], s[10:11], 0x0
	v_and_b32_e32 v3, 63, v2
	v_lshlrev_b32_e32 v0, 2, v3
	s_waitcnt lgkmcnt(0)
	s_add_u32 s4, s10, s22
	s_addc_u32 s5, s11, s23
	s_lshl_b32 s7, s6, 2
	s_add_u32 s10, s4, s7
	s_addc_u32 s11, s5, 0
	v_lshl_add_u64 v[8:9], s[10:11], 0, v[0:1]
	v_add_co_u32_e64 v34, s[40:41], s37, v8
	s_and_b64 s[14:15], vcc, exec
	s_nop 0
	v_addc_co_u32_e64 v35, s[40:41], 0, v9, s[40:41]
	s_movk_i32 s4, 0x70
	v_add_co_u32_e64 v36, s[40:41], s85, v8
	s_cselect_b32 s4, s4, 0x80
	s_nop 0
	v_addc_co_u32_e64 v37, s[40:41], 0, v9, s[40:41]
	s_add_u32 s14, s8, s4
	v_add_co_u32_e64 v26, s[40:41], s68, v8
	s_addc_u32 s15, s9, 0
	global_load_dword v6, v[36:37], off
	global_load_dword v7, v[36:37], off offset:1024
	global_load_dword v4, v[36:37], off offset:2048
	global_load_dword v5, v[36:37], off offset:3072
	v_addc_co_u32_e64 v27, s[40:41], 0, v9, s[40:41]
	global_load_dword v12, v[34:35], off offset:2048
	global_load_dword v13, v[34:35], off offset:3072
	global_load_dword v8, v[26:27], off
	s_load_dwordx2 s[14:15], s[14:15], 0x0
	v_readlane_b32 s4, v254, 41
	s_or_b32 s4, s6, s4
	global_load_dword v9, v[26:27], off offset:1024
	global_load_dword v10, v[26:27], off offset:2048
	global_load_dword v11, v[26:27], off offset:3072
	v_or_b32_e32 v26, s4, v3
	v_mov_b32_e32 v27, v1
	s_waitcnt lgkmcnt(0)
	v_lshl_add_u64 v[26:27], v[26:27], 2, s[14:15]
	global_load_dword v26, v[26:27], off
	s_nop 0
	global_load_dword v29, v0, s[10:11]
	global_load_dword v30, v0, s[10:11] offset:1024
	global_load_dword v31, v0, s[10:11] offset:2048
	global_load_dword v32, v0, s[10:11] offset:3072
	global_load_dword v28, v[36:37], off offset:-4096
	global_load_dword v27, v[34:35], off offset:1024
	v_ashrrev_i32_e32 v3, 6, v2
	v_lshl_add_u32 v25, v3, 9, 0
	ds_read_b128 v[34:37], v25 offset:27664
	ds_read_b128 v[38:41], v25 offset:27680
	ds_read_b128 v[42:45], v25 offset:27696
	ds_read_b128 v[46:49], v25 offset:27648
	s_mov_b32 s4, 0x3d800000
	v_lshl_add_u32 v2, v2, 2, 0
	v_add_u32_e32 v0, 0, v0
	v_readlane_b32 s5, v254, 42
	s_waitcnt vmcnt(15) lgkmcnt(2)
	v_pk_mul_f32 v[38:39], v[6:7], v[38:39]
	s_waitcnt vmcnt(13)
	v_pk_mul_f32 v[40:41], v[4:5], v[40:41]
	s_waitcnt vmcnt(11)
	v_pk_mul_f32 v[36:37], v[12:13], v[36:37]
	s_waitcnt vmcnt(9) lgkmcnt(1)
	v_pk_mul_f32 v[42:43], v[8:9], v[42:43]
	s_waitcnt vmcnt(5) lgkmcnt(0)
	v_fma_f32 v33, v29, v46, v26
	s_waitcnt vmcnt(4)
	v_fmac_f32_e32 v33, v30, v47
	s_waitcnt vmcnt(3)
	v_fmac_f32_e32 v33, v31, v48
	s_waitcnt vmcnt(2)
	v_fmac_f32_e32 v33, v32, v49
	s_waitcnt vmcnt(1)
	v_fmac_f32_e32 v33, v28, v34
	s_waitcnt vmcnt(0)
	v_fmac_f32_e32 v33, v27, v35
	v_add_f32_e32 v33, v33, v36
	v_add_f32_e32 v33, v33, v37
	v_add_f32_e32 v33, v33, v38
	v_add_f32_e32 v33, v33, v39
	v_add_f32_e32 v33, v33, v40
	v_add_f32_e32 v33, v33, v41
	v_add_f32_e32 v33, v33, v42
	v_pk_mul_f32 v[44:45], v[10:11], v[44:45]
	v_add_f32_e32 v33, v33, v43
	v_add_f32_e32 v33, v33, v44
	v_add_f32_e32 v33, v33, v45
	v_mul_f32_e64 v34, |v33|, s90
	v_exp_f32_e32 v38, v34
	v_min_f32_e32 v33, 0, v33
	s_nop 1
	s_nop 1
	ds_read_b128 v[34:37], v25 offset:27712
	s_nop 1
	s_nop 1
	v_add_f32_e32 v150, 1.0, v38
	s_nop 0
	v_add_f32_e32 v151, -1.0, v150
	v_log_f32_e32 v152, v150
	v_rcp_f32_e32 v153, v151
	s_nop 0
	v_mul_f32_e32 v152, 0x3f317218, v152
	v_mul_f32_e32 v153, v38, v153
	v_cmp_eq_f32_e32 vcc, 0, v151
	v_mul_f32_e32 v152, v152, v153
	s_nop 0
	v_cndmask_b32_e32 v42, v152, v38, vcc
	ds_read_b128 v[38:41], v25 offset:27728
	s_waitcnt lgkmcnt(1)
	v_fma_f32 v43, v29, v34, v26
	v_fmac_f32_e32 v43, v30, v35
	v_fmac_f32_e32 v43, v31, v36
	v_fmac_f32_e32 v43, v32, v37
	ds_read_b128 v[34:37], v25 offset:27744
	s_waitcnt lgkmcnt(1)
	v_fmac_f32_e32 v43, v28, v38
	v_fmac_f32_e32 v43, v27, v39
	v_pk_mul_f32 v[38:39], v[12:13], v[40:41]
	v_sub_f32_e32 v33, v33, v42
	v_add_f32_e32 v38, v43, v38
	v_add_f32_e32 v43, v38, v39
	ds_read_b128 v[38:41], v25 offset:27760
	s_waitcnt lgkmcnt(1)
	v_pk_mul_f32 v[34:35], v[6:7], v[34:35]
	v_fma_f32 v33, v33, s4, 0
	v_add_f32_e32 v34, v43, v34
	v_add_f32_e32 v43, v34, v35
	v_pk_mul_f32 v[34:35], v[4:5], v[36:37]
	s_nop 0
	v_add_f32_e32 v34, v43, v34
	v_add_f32_e32 v36, v34, v35
	s_waitcnt lgkmcnt(0)
	v_pk_mul_f32 v[34:35], v[8:9], v[38:39]
	s_nop 0
	v_add_f32_e32 v34, v36, v34
	v_add_f32_e32 v36, v34, v35
	v_pk_mul_f32 v[34:35], v[10:11], v[40:41]
	s_nop 0
	v_add_f32_e32 v34, v36, v34
	v_add_f32_e32 v34, v34, v35
	v_mul_f32_e64 v35, |v34|, s90
	v_exp_f32_e32 v38, v35
	v_min_f32_e32 v42, 0, v34
	s_nop 1
	s_nop 1
	s_nop 1
	ds_read_b128 v[34:37], v25 offset:27776
	s_nop 1
	s_nop 1
	v_add_f32_e32 v150, 1.0, v38
	s_nop 0
	v_add_f32_e32 v151, -1.0, v150
	v_log_f32_e32 v152, v150
	v_rcp_f32_e32 v153, v151
	s_nop 0
	v_mul_f32_e32 v152, 0x3f317218, v152
	v_mul_f32_e32 v153, v38, v153
	v_cmp_eq_f32_e32 vcc, 0, v151
	v_mul_f32_e32 v152, v152, v153
	s_nop 0
	v_cndmask_b32_e32 v43, v152, v38, vcc
	ds_read_b128 v[38:41], v25 offset:27792
	s_waitcnt lgkmcnt(1)
	v_fma_f32 v44, v29, v34, v26
	v_fmac_f32_e32 v44, v30, v35
	v_fmac_f32_e32 v44, v31, v36
	v_fmac_f32_e32 v44, v32, v37
	ds_read_b128 v[34:37], v25 offset:27808
	s_waitcnt lgkmcnt(1)
	v_fmac_f32_e32 v44, v28, v38
	v_fmac_f32_e32 v44, v27, v39
	v_pk_mul_f32 v[38:39], v[12:13], v[40:41]
	s_nop 0
	v_add_f32_e32 v38, v44, v38
	v_add_f32_e32 v44, v38, v39
	ds_read_b128 v[38:41], v25 offset:27824
	s_waitcnt lgkmcnt(1)
	v_pk_mul_f32 v[34:35], v[6:7], v[34:35]
	s_nop 0
	v_add_f32_e32 v34, v44, v34
	v_add_f32_e32 v44, v34, v35
	v_pk_mul_f32 v[34:35], v[4:5], v[36:37]
	s_nop 0
	v_add_f32_e32 v34, v44, v34
	v_add_f32_e32 v36, v34, v35
	s_waitcnt lgkmcnt(0)
	v_pk_mul_f32 v[34:35], v[8:9], v[38:39]
	s_nop 0
	v_add_f32_e32 v34, v36, v34
	v_add_f32_e32 v36, v34, v35
	v_pk_mul_f32 v[34:35], v[10:11], v[40:41]
	s_nop 0
	v_add_f32_e32 v34, v36, v34
	v_add_f32_e32 v35, v34, v35
	v_mul_f32_e64 v34, |v35|, s90
	v_exp_f32_e32 v40, v34
	v_sub_f32_e32 v34, v42, v43
	v_min_f32_e32 v35, 0, v35
	v_fmamk_f32 v34, v34, 0x3d800000, v33
	s_nop 1
	s_nop 1
	s_nop 1
	ds_read_b128 v[36:39], v25 offset:27840
	s_nop 1
	s_nop 1
	v_add_f32_e32 v150, 1.0, v40
	s_nop 0
	v_add_f32_e32 v151, -1.0, v150
	v_log_f32_e32 v152, v150
	v_rcp_f32_e32 v153, v151
	s_nop 0
	v_mul_f32_e32 v152, 0x3f317218, v152
	v_mul_f32_e32 v153, v40, v153
	v_cmp_eq_f32_e32 vcc, 0, v151
	v_mul_f32_e32 v152, v152, v153
	s_nop 0
	v_cndmask_b32_e32 v44, v152, v40, vcc
	ds_read_b128 v[40:43], v25 offset:27856
	s_waitcnt lgkmcnt(1)
	v_fma_f32 v45, v29, v36, v26
	v_fmac_f32_e32 v45, v30, v37
	v_fmac_f32_e32 v45, v31, v38
	v_fmac_f32_e32 v45, v32, v39
	ds_read_b128 v[36:39], v25 offset:27872
	s_waitcnt lgkmcnt(1)
	v_fmac_f32_e32 v45, v28, v40
	v_fmac_f32_e32 v45, v27, v41
	v_pk_mul_f32 v[40:41], v[12:13], v[42:43]
	v_sub_f32_e32 v35, v35, v44
	v_add_f32_e32 v40, v45, v40
	v_add_f32_e32 v45, v40, v41
	ds_read_b128 v[40:43], v25 offset:27888
	s_waitcnt lgkmcnt(1)
	v_pk_mul_f32 v[36:37], v[6:7], v[36:37]
	v_fmamk_f32 v35, v35, 0x3d800000, v34
	v_add_f32_e32 v36, v45, v36
	v_add_f32_e32 v45, v36, v37
	v_pk_mul_f32 v[36:37], v[4:5], v[38:39]
	s_nop 0
	v_add_f32_e32 v36, v45, v36
	v_add_f32_e32 v38, v36, v37
	s_waitcnt lgkmcnt(0)
	v_pk_mul_f32 v[36:37], v[8:9], v[40:41]
	s_nop 0
	v_add_f32_e32 v36, v38, v36
	v_add_f32_e32 v38, v36, v37
	v_pk_mul_f32 v[36:37], v[10:11], v[42:43]
	s_nop 0
	v_add_f32_e32 v36, v38, v36
	v_add_f32_e32 v36, v36, v37
	v_mul_f32_e64 v37, |v36|, s90
	v_exp_f32_e32 v40, v37
	v_min_f32_e32 v44, 0, v36
	s_nop 1
	s_nop 1
	s_nop 1
	ds_read_b128 v[36:39], v25 offset:27904
	s_nop 1
	s_nop 1
	v_add_f32_e32 v150, 1.0, v40
	s_nop 0
	v_add_f32_e32 v151, -1.0, v150
	v_log_f32_e32 v152, v150
	v_rcp_f32_e32 v153, v151
	s_nop 0
	v_mul_f32_e32 v152, 0x3f317218, v152
	v_mul_f32_e32 v153, v40, v153
	v_cmp_eq_f32_e32 vcc, 0, v151
	v_mul_f32_e32 v152, v152, v153
	s_nop 0
	v_cndmask_b32_e32 v45, v152, v40, vcc
	ds_read_b128 v[40:43], v25 offset:27920
	s_waitcnt lgkmcnt(1)
	v_fma_f32 v46, v29, v36, v26
	v_fmac_f32_e32 v46, v30, v37
	v_fmac_f32_e32 v46, v31, v38
	v_fmac_f32_e32 v46, v32, v39
	ds_read_b128 v[36:39], v25 offset:27936
	s_waitcnt lgkmcnt(1)
	v_fmac_f32_e32 v46, v28, v40
	v_fmac_f32_e32 v46, v27, v41
	v_pk_mul_f32 v[40:41], v[12:13], v[42:43]
	s_nop 0
	v_add_f32_e32 v40, v46, v40
	v_add_f32_e32 v46, v40, v41
	ds_read_b128 v[40:43], v25 offset:27952
	s_waitcnt lgkmcnt(1)
	v_pk_mul_f32 v[36:37], v[6:7], v[36:37]
	s_nop 0
	v_add_f32_e32 v36, v46, v36
	v_add_f32_e32 v46, v36, v37
	v_pk_mul_f32 v[36:37], v[4:5], v[38:39]
	s_nop 0
	v_add_f32_e32 v36, v46, v36
	v_add_f32_e32 v38, v36, v37
	s_waitcnt lgkmcnt(0)
	v_pk_mul_f32 v[36:37], v[8:9], v[40:41]
	s_nop 0
	v_add_f32_e32 v36, v38, v36
	v_add_f32_e32 v38, v36, v37
	v_pk_mul_f32 v[36:37], v[10:11], v[42:43]
	s_nop 0
	v_add_f32_e32 v36, v38, v36
	v_add_f32_e32 v37, v36, v37
	v_mul_f32_e64 v36, |v37|, s90
	v_exp_f32_e32 v42, v36
	v_sub_f32_e32 v36, v44, v45
	v_min_f32_e32 v37, 0, v37
	v_fmamk_f32 v36, v36, 0x3d800000, v35
	s_nop 1
	s_nop 1
	s_nop 1
	ds_read_b128 v[38:41], v25 offset:27968
	s_nop 1
	s_nop 1
	v_add_f32_e32 v150, 1.0, v42
	s_nop 0
	v_add_f32_e32 v151, -1.0, v150
	v_log_f32_e32 v152, v150
	v_rcp_f32_e32 v153, v151
	s_nop 0
	v_mul_f32_e32 v152, 0x3f317218, v152
	v_mul_f32_e32 v153, v42, v153
	v_cmp_eq_f32_e32 vcc, 0, v151
	v_mul_f32_e32 v152, v152, v153
	s_nop 0
	v_cndmask_b32_e32 v46, v152, v42, vcc
	ds_read_b128 v[42:45], v25 offset:27984
	s_waitcnt lgkmcnt(1)
	v_fma_f32 v47, v29, v38, v26
	v_fmac_f32_e32 v47, v30, v39
	v_fmac_f32_e32 v47, v31, v40
	v_fmac_f32_e32 v47, v32, v41
	ds_read_b128 v[38:41], v25 offset:28000
	s_waitcnt lgkmcnt(1)
	v_fmac_f32_e32 v47, v28, v42
	v_fmac_f32_e32 v47, v27, v43
	v_pk_mul_f32 v[42:43], v[12:13], v[44:45]
	v_sub_f32_e32 v37, v37, v46
	v_add_f32_e32 v42, v47, v42
	v_add_f32_e32 v47, v42, v43
	ds_read_b128 v[42:45], v25 offset:28016
	s_waitcnt lgkmcnt(1)
	v_pk_mul_f32 v[38:39], v[6:7], v[38:39]
	v_fmamk_f32 v37, v37, 0x3d800000, v36
	v_add_f32_e32 v38, v47, v38
	v_add_f32_e32 v47, v38, v39
	v_pk_mul_f32 v[38:39], v[4:5], v[40:41]
	s_nop 0
	v_add_f32_e32 v38, v47, v38
	v_add_f32_e32 v40, v38, v39
	s_waitcnt lgkmcnt(0)
	v_pk_mul_f32 v[38:39], v[8:9], v[42:43]
	s_nop 0
	v_add_f32_e32 v38, v40, v38
	v_add_f32_e32 v40, v38, v39
	v_pk_mul_f32 v[38:39], v[10:11], v[44:45]
	s_nop 0
	v_add_f32_e32 v38, v40, v38
	v_add_f32_e32 v38, v38, v39
	v_mul_f32_e64 v39, |v38|, s90
	v_exp_f32_e32 v52, v39
	v_min_f32_e32 v53, 0, v38
	s_nop 1
	s_nop 0
	s_nop 0
	s_nop 0
	s_nop 0
	s_nop 0
	s_nop 1
	ds_read_b128 v[38:41], v25 offset:28032
	s_nop 1
	s_nop 1
	v_add_f32_e32 v150, 1.0, v52
	s_nop 0
	v_add_f32_e32 v151, -1.0, v150
	v_log_f32_e32 v152, v150
	v_rcp_f32_e32 v153, v151
	s_nop 0
	v_mul_f32_e32 v152, 0x3f317218, v152
	v_mul_f32_e32 v153, v52, v153
	v_cmp_eq_f32_e32 vcc, 0, v151
	v_mul_f32_e32 v152, v152, v153
	s_nop 0
	v_cndmask_b32_e32 v46, v152, v52, vcc
	ds_read_b128 v[42:45], v25 offset:28048
	s_waitcnt lgkmcnt(1)
	v_fma_f32 v47, v29, v38, v26
	v_fmac_f32_e32 v47, v30, v39
	v_fmac_f32_e32 v47, v31, v40
	v_fmac_f32_e32 v47, v32, v41
	ds_read_b128 v[38:41], v25 offset:28064
	s_waitcnt lgkmcnt(1)
	v_fmac_f32_e32 v47, v28, v42
	v_fmac_f32_e32 v47, v27, v43
	v_pk_mul_f32 v[42:43], v[12:13], v[44:45]
	s_nop 0
	v_add_f32_e32 v42, v47, v42
	v_add_f32_e32 v47, v42, v43
	ds_read_b128 v[42:45], v25 offset:28080
	s_waitcnt lgkmcnt(1)
	v_pk_mul_f32 v[38:39], v[6:7], v[38:39]
	s_nop 0
	v_add_f32_e32 v38, v47, v38
	v_add_f32_e32 v47, v38, v39
	v_pk_mul_f32 v[38:39], v[4:5], v[40:41]
	s_nop 0
	v_add_f32_e32 v38, v47, v38
	v_add_f32_e32 v40, v38, v39
	s_waitcnt lgkmcnt(0)
	v_pk_mul_f32 v[38:39], v[8:9], v[42:43]
	s_nop 0
	v_add_f32_e32 v38, v40, v38
	v_add_f32_e32 v40, v38, v39
	v_pk_mul_f32 v[38:39], v[10:11], v[44:45]
	s_nop 0
	v_add_f32_e32 v38, v40, v38
	v_add_f32_e32 v38, v38, v39
	v_mul_f32_e64 v39, |v38|, s90
	v_exp_f32_e32 v52, v39
	v_sub_f32_e32 v39, v53, v46
	v_min_f32_e32 v54, 0, v38
	v_fmamk_f32 v53, v39, 0x3d800000, v37
	s_nop 1
	s_nop 0
	s_nop 0
	s_nop 0
	s_nop 0
	s_nop 0
	s_nop 1
	ds_read_b128 v[38:41], v25 offset:28096
	s_nop 1
	s_nop 1
	v_add_f32_e32 v150, 1.0, v52
	s_nop 0
	v_add_f32_e32 v151, -1.0, v150
	v_log_f32_e32 v152, v150
	v_rcp_f32_e32 v153, v151
	s_nop 0
	v_mul_f32_e32 v152, 0x3f317218, v152
	v_mul_f32_e32 v153, v52, v153
	v_cmp_eq_f32_e32 vcc, 0, v151
	v_mul_f32_e32 v152, v152, v153
	s_nop 0
	v_cndmask_b32_e32 v46, v152, v52, vcc
	ds_read_b128 v[42:45], v25 offset:28112
	s_waitcnt lgkmcnt(1)
	v_fmac_f32_e32 v26, v29, v38
	v_fmac_f32_e32 v26, v30, v39
	v_fmac_f32_e32 v26, v31, v40
	v_fmac_f32_e32 v26, v32, v41
	s_waitcnt lgkmcnt(0)
	v_fmac_f32_e32 v26, v28, v42
	ds_read_b128 v[28:31], v25 offset:28128
	ds_read_b128 v[38:41], v25 offset:28144
	v_fmac_f32_e32 v26, v27, v43
	v_pk_mul_f32 v[12:13], v[12:13], v[44:45]
	s_waitcnt lgkmcnt(1)
	v_pk_mul_f32 v[6:7], v[6:7], v[28:29]
	v_add_f32_e32 v12, v26, v12
	v_add_f32_e32 v12, v12, v13
	v_add_f32_e32 v6, v12, v6
	v_add_f32_e32 v6, v6, v7
	v_pk_mul_f32 v[4:5], v[4:5], v[30:31]
	s_nop 0
	v_add_f32_e32 v4, v6, v4
	v_add_f32_e32 v6, v4, v5
	s_waitcnt lgkmcnt(0)
	v_pk_mul_f32 v[4:5], v[8:9], v[38:39]
	s_nop 0
	v_add_f32_e32 v4, v6, v4
	v_add_f32_e32 v6, v4, v5
	v_pk_mul_f32 v[4:5], v[10:11], v[40:41]
	s_nop 0
	v_add_f32_e32 v4, v6, v4
	v_add_f32_e32 v4, v4, v5
	v_mul_f32_e64 v5, |v4|, s90
	v_exp_f32_e32 v25, v5
	v_sub_f32_e32 v5, v54, v46
	v_min_f32_e32 v31, 0, v4
	v_fmamk_f32 v30, v5, 0x3d800000, v53
	s_nop 1
	s_nop 0
	s_nop 0
	s_nop 0
	s_nop 0
	s_nop 0
	s_nop 1
	s_nop 1
	s_nop 1
	v_add_f32_e32 v150, 1.0, v25
	s_nop 0
	v_add_f32_e32 v151, -1.0, v150
	v_log_f32_e32 v152, v150
	v_rcp_f32_e32 v153, v151
	s_nop 0
	v_mul_f32_e32 v152, 0x3f317218, v152
	v_mul_f32_e32 v153, v25, v153
	v_cmp_eq_f32_e32 vcc, 0, v151
	v_mul_f32_e32 v152, v152, v153
	s_nop 0
	v_cndmask_b32_e32 v4, v152, v25, vcc
	v_sub_f32_e32 v4, v31, v4
	v_fmamk_f32 v5, v4, 0x3d800000, v30
	ds_write_b32 v2, v5 offset:31744
	s_waitcnt lgkmcnt(0)
	s_barrier
	ds_read2st64_b32 v[6:7], v0 offset0:124 offset1:125
	ds_read2st64_b32 v[8:9], v0 offset0:126 offset1:127
	ds_read2st64_b32 v[10:11], v0 offset0:128 offset1:129
	ds_read2st64_b32 v[12:13], v0 offset0:130 offset1:131
	v_cmp_lt_i32_e32 vcc, 0, v3
	s_waitcnt lgkmcnt(3)
	v_add_f32_e32 v0, 0, v6
	s_waitcnt lgkmcnt(0)
	v_cndmask_b32_e32 v2, 0, v0, vcc
	v_add_f32_e32 v4, v7, v2
	v_cmp_lt_i32_e32 vcc, 1, v3
	v_add_f32_e32 v0, v0, v7
	v_add_f32_e32 v0, v0, v8
	v_cndmask_b32_e32 v2, v2, v4, vcc
	v_add_f32_e32 v4, v8, v2
	v_cmp_lt_i32_e32 vcc, 2, v3
	v_add_f32_e32 v0, v0, v9
	v_add_f32_e32 v0, v0, v10
	v_cndmask_b32_e32 v2, v2, v4, vcc
	v_add_f32_e32 v4, v9, v2
	v_cmp_lt_i32_e32 vcc, 3, v3
	v_add_f32_e32 v0, v0, v11
	v_lshlrev_b32_e32 v7, 16, v21
	v_cndmask_b32_e32 v2, v2, v4, vcc
	v_add_f32_e32 v4, v10, v2
	v_cmp_lt_i32_e32 vcc, 4, v3
	v_lshlrev_b32_e32 v9, 16, v22
	v_lshlrev_b32_e32 v8, 16, v17
	v_cndmask_b32_e32 v2, v2, v4, vcc
	v_add_f32_e32 v4, v11, v2
	v_cmp_lt_i32_e32 vcc, 5, v3
	v_lshlrev_b32_e32 v11, 16, v24
	v_lshlrev_b32_e32 v10, 16, v20
	v_cndmask_b32_e32 v2, v2, v4, vcc
	v_add_f32_e32 v4, v12, v2
	v_cmp_lt_i32_e32 vcc, 6, v3
	s_barrier
	s_nop 0
	v_cndmask_b32_e32 v2, v2, v4, vcc
	v_add_f32_e32 v4, v13, v2
	v_cmp_lt_i32_e32 vcc, 7, v3
	s_nop 1
	v_cndmask_b32_e32 v3, v2, v4, vcc
	v_add_f32_e32 v4, v0, v12
	v_mov_b32_e32 v2, v13
	v_add_f32_e32 v6, v33, v3
	v_add_f32_e32 v25, v34, v3
	v_add_f32_e32 v26, v35, v3
	v_add_f32_e32 v27, v36, v3
	v_add_f32_e32 v28, v3, v37
	v_add_f32_e32 v29, v3, v53
	v_add_f32_e32 v30, v3, v30
	v_pk_add_f32 v[2:3], v[4:5], v[2:3]
	v_mov_b32_e32 v80, v6
	v_mov_b32_e32 v81, v25
	v_mov_b32_e32 v82, v26
	v_mov_b32_e32 v83, v27
	v_mov_b32_e32 v84, v28
	v_mov_b32_e32 v85, v29
	v_mov_b32_e32 v86, v30
	v_mov_b32_e32 v87, v3
	v_lshlrev_b32_e32 v88, 5, v202
	s_lshl_b32 s98, s30, 14
	s_add_u32 s98, s98, 0x4f28000
	s_add_u32 s98, s100, s98
	s_addc_u32 s99, s101, 0
	global_store_dwordx4 v88, v[80:83], s[98:99]
	global_store_dwordx4 v88, v[84:87], s[98:99] offset:16
	v_cmp_gt_i32_e32 vcc, 64, v18
	v_sub_f32_e32 v0, v2, v6
	v_mul_f32_e32 v0, 0x3fb8aa3b, v0
	v_exp_f32_e32 v4, v0
	v_sub_f32_e32 v0, v2, v25
	v_mul_f32_e32 v0, 0x3fb8aa3b, v0
	v_exp_f32_e32 v5, v0
	v_sub_f32_e32 v0, v2, v26
	v_lshlrev_b32_e32 v6, 16, v16
	v_mul_f32_e32 v0, 0x3fb8aa3b, v0
	v_pk_mul_f32 v[4:5], v[4:5], v[6:7]
	v_exp_f32_e32 v6, v0
	v_sub_f32_e32 v0, v2, v27
	v_mul_f32_e32 v0, 0x3fb8aa3b, v0
	v_exp_f32_e32 v7, v0
	v_sub_f32_e32 v0, v2, v28
	v_mul_f32_e32 v0, 0x3fb8aa3b, v0
	v_cvt_pk_bf16_f32 v4, v4, v5
	v_pk_mul_f32 v[6:7], v[6:7], v[8:9]
	v_exp_f32_e32 v8, v0
	v_sub_f32_e32 v0, v2, v29
	v_mul_f32_e32 v0, 0x3fb8aa3b, v0
	v_exp_f32_e32 v9, v0
	v_sub_f32_e32 v0, v2, v30
	v_cvt_pk_bf16_f32 v5, v6, v7
	v_lshlrev_b32_e32 v7, 16, v23
	v_lshlrev_b32_e32 v6, 16, v19
	v_mul_f32_e32 v0, 0x3fb8aa3b, v0
	v_pk_mul_f32 v[6:7], v[8:9], v[6:7]
	v_exp_f32_e32 v8, v0
	v_sub_f32_e32 v0, v2, v3
	v_mul_f32_e32 v0, 0x3fb8aa3b, v0
	v_exp_f32_e32 v9, v0
	v_mul_u32_u24_e32 v0, 0x90, v15
	v_lshlrev_b32_e32 v3, 4, v14
	v_cvt_pk_bf16_f32 v6, v6, v7
	v_pk_mul_f32 v[8:9], v[8:9], v[10:11]
	v_add3_u32 v0, 0, v0, v3
	v_cvt_pk_bf16_f32 v7, v8, v9
	ds_write_b128 v0, v[4:7]
	s_and_saveexec_b64 s[14:15], vcc
	s_cbranch_execz .LBB0_677
	v_mul_f32_e32 v0, 0x3fb8aa3b, v2
	s_lshl_b64 s[6:7], s[30:31], 8
	v_readlane_b32 s4, v254, 53
	v_exp_f32_e32 v0, v0
	v_readlane_b32 s5, v254, 54
	s_add_u32 s6, s4, s6
	s_addc_u32 s7, s5, s7
	v_ashrrev_i32_e32 v19, 31, v18
	v_lshl_add_u64 v[2:3], v[18:19], 2, s[6:7]
	global_store_dword v[2:3], v0, off
